# S5 output-matrix fragments stored in MFMA fragment order by the prep phase, so each of the 4 fragment loads per SSM item is one contiguous 1 KB access (8 lines instead of 16 half-lines)
# speedup vs baseline: 1.0612x; 1.0001x over previous
.LBB0_113:
	v_ashrrev_i32_e32 v8, 16, v1
	v_ashrrev_i32_e32 v9, 31, v8
	v_and_b32_e32 v2, 0xffff, v1
	v_lshlrev_b64 v[10:11], 18, v[8:9]
	v_lshl_or_b32 v10, v2, 2, v10
	v_lshl_add_u64 v[12:13], s[38:39], 0, v[10:11]
	v_lshl_add_u64 v[10:11], s[40:41], 0, v[10:11]
	global_load_dword v7, v[10:11], off
	s_nop 0
	global_load_dword v10, v[12:13], off
	v_and_b32_e32 v2, 0x1ff80, v6
	v_mul_hi_i32_i24_e32 v9, 0x98000, v8
	v_mul_i32_i24_e32 v8, 0x98000, v8
	v_lshlrev_b32_e32 v2, 1, v2
	v_lshl_add_u64 v[8:9], s[86:87], 0, v[8:9]
	v_and_b32_e32 v202, 0xfc00, v1
	v_bfe_u32 v204, v1, 4, 2
	v_lshl_or_b32 v202, v204, 8, v202
	v_bfe_u32 v204, v1, 2, 2
	v_lshl_or_b32 v202, v204, 6, v202
	v_bfe_u32 v204, v1, 6, 4
	v_lshl_or_b32 v202, v204, 2, v202
	v_and_b32_e32 v204, 3, v1
	v_or_b32_e32 v202, v202, v204
	v_lshlrev_b32_e32 v202, 2, v202
	v_mov_b32_e32 v203, 0
	v_lshl_add_u64 v[8:9], v[8:9], 0, v[202:203]
	s_add_i32 s3, s3, s10
	v_add_co_u32_e32 v8, vcc, 0xf658000, v8
	v_add_u32_e32 v6, s0, v6
	v_add_u32_e32 v1, s1, v1
	s_cmpk_lt_i32 s3, 0x100
	v_addc_co_u32_e32 v9, vcc, 0, v9, vcc
	s_waitcnt vmcnt(1)
	v_xor_b32_e32 v2, 0x80000000, v7
	s_waitcnt vmcnt(0)
	v_cvt_pk_bf16_f32 v2, v10, v2
	global_store_dword v[8:9], v2, off
	s_cbranch_scc1 .LBB0_113

.LBB0_678:
	v_and_b32_e32 v0, 3, v6
	v_lshrrev_b32_e32 v1, 1, v6
	v_and_or_b32 v0, v1, 12, v0
	v_and_b32_e32 v1, 4, v6
	v_mov_b32_e32 v2, s24
	v_mov_b32_e32 v3, s23
	v_cmp_eq_u32_e32 vcc, 0, v1
	s_lshl_b32 s22, s25, 4
	v_and_b32_e32 v160, 15, v6
	v_cndmask_b32_e32 v1, v2, v3, vcc
	v_add_u32_e32 v2, v0, v1
	v_mov_b64_e32 v[0:1], s[86:87]
	v_mad_i64_i32 v[0:1], s[0:1], v2, s66, v[0:1]
	v_lshlrev_b32_e32 v2, 4, v160
	v_lshl_or_b32 v2, s22, 8, v2
	v_mov_b32_e32 v3, v173
	v_lshl_add_u64 v[2:3], s[34:35], 0, v[2:3]
	v_and_b32_e32 v34, 48, v6
	v_mov_b32_e32 v35, v173
	v_lshl_add_u64 v[2:3], v[34:35], 4, v[2:3]
	global_load_dword v159, v[4:5], off
	global_load_dwordx4 v[80:83], v[2:3], off
	global_load_dwordx4 v[76:79], v[2:3], off offset:1024
	global_load_dwordx4 v[72:75], v[2:3], off offset:2048
	global_load_dwordx4 v[68:71], v[2:3], off offset:3072
	v_lshrrev_b32_e32 v2, 2, v6
	v_and_b32_e32 v4, 12, v2
	v_or_b32_e32 v2, s18, v4
	v_readlane_b32 s44, v237, 4
	v_or_b32_e32 v2, s22, v2
	v_mov_b32_e32 v3, v173
	v_readlane_b32 s50, v237, 10
	v_readlane_b32 s51, v237, 11
	v_lshlrev_b32_e32 v7, 3, v36
	s_lshl_b32 s94, s25, 5
	v_lshl_add_u64 v[2:3], v[2:3], 2, s[50:51]
	v_lshl_add_u64 v[0:1], v[0:1], 0, s[94:95]
	global_load_dwordx4 v[64:67], v[2:3], off
	v_lshlrev_b32_e32 v2, 1, v7
	v_mov_b32_e32 v3, v173
	s_add_u32 s0, s86, s94
	v_lshl_add_u64 v[2:3], v[0:1], 0, v[2:3]
	s_addc_u32 s1, s87, 0
	v_lshlrev_b32_e32 v120, 1, v4
	v_mov_b32_e32 v121, v173
	v_lshl_add_u64 v[0:1], s[0:1], 0, v[120:121]
	v_add_co_u32_e32 v4, vcc, s92, v2
	v_add_u32_e32 v16, s23, v160
	s_nop 0
	v_addc_co_u32_e32 v5, vcc, 0, v3, vcc
	v_mad_i64_i32 v[6:7], s[0:1], v16, s66, v[0:1]
	v_add_co_u32_e32 v8, vcc, s92, v6
	v_add_u32_e32 v17, s24, v160
	s_nop 0
	v_addc_co_u32_e32 v9, vcc, 0, v7, vcc
	global_load_dwordx4 v[48:51], v[4:5], off
	global_load_dwordx2 v[152:153], v[6:7], off offset:2048
	v_mad_i64_i32 v[4:5], s[0:1], v17, s66, v[0:1]
	v_add_co_u32_e32 v6, vcc, s92, v4
	s_mov_b32 s0, 0x32000
	s_nop 0
	v_addc_co_u32_e32 v7, vcc, 0, v5, vcc
	v_or_b32_e32 v10, 16, v160
	global_load_dwordx2 v[156:157], v[8:9], off
	global_load_dwordx2 v[154:155], v[6:7], off
	global_load_dwordx2 v[112:113], v[4:5], off offset:2048
	v_add_co_u32_e32 v4, vcc, s0, v2
	v_add_u32_e32 v18, s23, v10
	s_nop 0
	v_addc_co_u32_e32 v5, vcc, 0, v3, vcc
	v_mad_i64_i32 v[6:7], s[0:1], v18, s66, v[0:1]
	v_add_co_u32_e32 v8, vcc, s92, v6
	v_add_u32_e32 v33, s24, v10
	s_nop 0
	v_addc_co_u32_e32 v9, vcc, 0, v7, vcc
	global_load_dwordx4 v[108:111], v[4:5], off
	global_load_dwordx2 v[144:145], v[6:7], off offset:2048
	v_mad_i64_i32 v[4:5], s[0:1], v33, s66, v[0:1]
	v_add_co_u32_e32 v6, vcc, 0x2000, v4
	s_mov_b64 s[0:1], 0x2000
	s_nop 0
	v_addc_co_u32_e32 v7, vcc, 0, v5, vcc
	global_load_dwordx2 v[146:147], v[8:9], off
	global_load_dwordx2 v[142:143], v[6:7], off
	global_load_dwordx2 v[140:141], v[4:5], off offset:2048
	v_cndmask_b32_e64 v4, 0, 1, s[42:43]
	v_lshl_add_u64 v[2:3], v[2:3], 0, s[0:1]
	v_cmp_ne_u32_e64 s[0:1], 1, v4
	v_or_b32_e32 v4, 32, v160
	s_andn2_b64 vcc, exec, s[42:43]
	v_add_u32_e32 v165, s23, v4
	v_add_u32_e32 v164, s24, v4
	v_readlane_b32 s45, v237, 5
	v_readlane_b32 s46, v237, 6
	v_readlane_b32 s47, v237, 7
	v_readlane_b32 s48, v237, 8
	v_readlane_b32 s49, v237, 9
	v_readlane_b32 s52, v237, 12
	v_readlane_b32 s53, v237, 13
	v_readlane_b32 s54, v237, 14
	v_readlane_b32 s55, v237, 15
	v_readlane_b32 s56, v237, 16
	v_readlane_b32 s57, v237, 17
	v_readlane_b32 s58, v237, 18
	v_readlane_b32 s59, v237, 19
	s_cbranch_vccnz .LBB0_680
	v_add_co_u32_e32 v4, vcc, 0x60000, v2
	v_mad_i64_i32 v[6:7], s[26:27], v165, s66, v[0:1]
	s_nop 0
	v_addc_co_u32_e32 v5, vcc, 0, v3, vcc
	v_add_co_u32_e32 v8, vcc, 0x2000, v6
	global_load_dwordx4 v[104:107], v[4:5], off
	global_load_dwordx2 v[136:137], v[6:7], off offset:2048
	v_addc_co_u32_e32 v9, vcc, 0, v7, vcc
	v_mad_i64_i32 v[4:5], s[26:27], v164, s66, v[0:1]
	v_add_co_u32_e32 v6, vcc, 0x2000, v4
	s_nop 1
	v_addc_co_u32_e32 v7, vcc, 0, v5, vcc
	global_load_dwordx2 v[138:139], v[8:9], off
	global_load_dwordx2 v[134:135], v[6:7], off
	global_load_dwordx2 v[132:133], v[4:5], off offset:2048

.LBB0_754:
	v_and_b32_e32 v0, 3, v6
	v_lshrrev_b32_e32 v1, 1, v6
	v_and_or_b32 v0, v1, 12, v0
	v_and_b32_e32 v1, 4, v6
	v_mov_b32_e32 v2, s24
	v_mov_b32_e32 v3, s23
	v_cmp_eq_u32_e32 vcc, 0, v1
	s_lshl_b32 s22, s25, 4
	v_and_b32_e32 v160, 15, v6
	v_cndmask_b32_e32 v1, v2, v3, vcc
	v_add_u32_e32 v2, v0, v1
	v_mov_b64_e32 v[0:1], s[86:87]
	v_mad_i64_i32 v[0:1], s[0:1], v2, s66, v[0:1]
	v_lshlrev_b32_e32 v2, 4, v160
	v_lshl_or_b32 v2, s22, 8, v2
	v_mov_b32_e32 v3, v173
	v_lshl_add_u64 v[2:3], s[34:35], 0, v[2:3]
	v_and_b32_e32 v34, 48, v6
	v_mov_b32_e32 v35, v173
	v_lshl_add_u64 v[2:3], v[34:35], 4, v[2:3]
	global_load_dword v157, v[4:5], off
	global_load_dwordx4 v[80:83], v[2:3], off
	global_load_dwordx4 v[76:79], v[2:3], off offset:1024
	global_load_dwordx4 v[72:75], v[2:3], off offset:2048
	global_load_dwordx4 v[68:71], v[2:3], off offset:3072
	v_lshrrev_b32_e32 v2, 2, v6
	v_and_b32_e32 v4, 12, v2
	v_or_b32_e32 v2, s20, v4
	v_readlane_b32 s4, v237, 4
	v_or_b32_e32 v2, s22, v2
	v_mov_b32_e32 v3, v173
	v_readlane_b32 s10, v237, 10
	v_readlane_b32 s11, v237, 11
	v_lshlrev_b32_e32 v7, 3, v36
	s_lshl_b32 s94, s25, 5
	v_lshl_add_u64 v[2:3], v[2:3], 2, s[10:11]
	v_lshl_add_u64 v[0:1], v[0:1], 0, s[94:95]
	global_load_dwordx4 v[64:67], v[2:3], off
	v_lshlrev_b32_e32 v2, 1, v7
	v_mov_b32_e32 v3, v173
	s_add_u32 s0, s86, s94
	v_lshl_add_u64 v[2:3], v[0:1], 0, v[2:3]
	s_addc_u32 s1, s87, 0
	v_lshlrev_b32_e32 v120, 1, v4
	v_mov_b32_e32 v121, v173
	v_lshl_add_u64 v[0:1], s[0:1], 0, v[120:121]
	v_add_co_u32_e32 v4, vcc, s92, v2
	v_add_u32_e32 v16, s23, v160
	s_nop 0
	v_addc_co_u32_e32 v5, vcc, 0, v3, vcc
	v_mad_i64_i32 v[6:7], s[0:1], v16, s66, v[0:1]
	v_add_co_u32_e32 v8, vcc, s92, v6
	v_add_u32_e32 v17, s24, v160
	s_nop 0
	v_addc_co_u32_e32 v9, vcc, 0, v7, vcc
	global_load_dwordx4 v[48:51], v[4:5], off
	global_load_dwordx2 v[152:153], v[6:7], off offset:2048
	v_mad_i64_i32 v[4:5], s[0:1], v17, s66, v[0:1]
	v_add_co_u32_e32 v6, vcc, s92, v4
	s_mov_b32 s0, 0x32000
	s_nop 0
	v_addc_co_u32_e32 v7, vcc, 0, v5, vcc
	v_or_b32_e32 v10, 16, v160
	global_load_dwordx2 v[112:113], v[4:5], off offset:2048
	v_add_co_u32_e32 v4, vcc, s0, v2
	v_add_u32_e32 v18, s23, v10
	s_nop 0
	v_addc_co_u32_e32 v5, vcc, 0, v3, vcc
	v_mad_i64_i32 v[6:7], s[0:1], v18, s66, v[0:1]
	v_add_co_u32_e32 v8, vcc, s92, v6
	v_add_u32_e32 v33, s24, v10
	s_nop 0
	v_addc_co_u32_e32 v9, vcc, 0, v7, vcc
	global_load_dwordx4 v[108:111], v[4:5], off
	global_load_dwordx2 v[144:145], v[6:7], off offset:2048
	v_mad_i64_i32 v[4:5], s[0:1], v33, s66, v[0:1]
	v_add_co_u32_e32 v6, vcc, 0x2000, v4
	s_mov_b64 s[0:1], 0x2000
	s_nop 0
	v_addc_co_u32_e32 v7, vcc, 0, v5, vcc
	global_load_dwordx2 v[140:141], v[4:5], off offset:2048
	v_cndmask_b32_e64 v4, 0, 1, s[44:45]
	v_lshl_add_u64 v[2:3], v[2:3], 0, s[0:1]
	v_cmp_ne_u32_e64 s[0:1], 1, v4
	v_or_b32_e32 v4, 32, v160
	s_andn2_b64 vcc, exec, s[44:45]
	v_add_u32_e32 v165, s23, v4
	v_add_u32_e32 v164, s24, v4
	v_readlane_b32 s5, v237, 5
	v_readlane_b32 s6, v237, 6
	v_readlane_b32 s7, v237, 7
	v_readlane_b32 s8, v237, 8
	v_readlane_b32 s9, v237, 9
	v_readlane_b32 s12, v237, 12
	v_readlane_b32 s13, v237, 13
	v_readlane_b32 s14, v237, 14
	v_readlane_b32 s15, v237, 15
	v_readlane_b32 s16, v237, 16
	v_readlane_b32 s17, v237, 17
	v_readlane_b32 s18, v237, 18
	v_readlane_b32 s19, v237, 19
	s_cbranch_vccnz .LBB0_756
	v_add_co_u32_e32 v4, vcc, 0x60000, v2
	v_mad_i64_i32 v[6:7], s[26:27], v165, s66, v[0:1]
	s_nop 0
	v_addc_co_u32_e32 v5, vcc, 0, v3, vcc
	v_add_co_u32_e32 v8, vcc, 0x2000, v6
	global_load_dwordx4 v[104:107], v[4:5], off
	global_load_dwordx2 v[136:137], v[6:7], off offset:2048
	v_addc_co_u32_e32 v9, vcc, 0, v7, vcc
	v_mad_i64_i32 v[4:5], s[26:27], v164, s66, v[0:1]
	v_add_co_u32_e32 v6, vcc, 0x2000, v4
	s_nop 1
	v_addc_co_u32_e32 v7, vcc, 0, v5, vcc
	global_load_dwordx2 v[132:133], v[4:5], off offset:2048

.LBB0_780:
	v_and_b32_e32 v0, 3, v6
	v_lshrrev_b32_e32 v1, 1, v6
	v_and_or_b32 v0, v1, 12, v0
	v_and_b32_e32 v1, 4, v6
	v_mov_b32_e32 v2, s24
	v_mov_b32_e32 v3, s23
	v_cmp_eq_u32_e32 vcc, 0, v1
	s_lshl_b32 s22, s25, 4
	v_and_b32_e32 v160, 15, v6
	v_cndmask_b32_e32 v1, v2, v3, vcc
	v_add_u32_e32 v2, v0, v1
	v_mov_b64_e32 v[0:1], s[86:87]
	v_mad_i64_i32 v[0:1], s[0:1], v2, s66, v[0:1]
	v_lshlrev_b32_e32 v2, 4, v160
	v_lshl_or_b32 v2, s22, 8, v2
	v_mov_b32_e32 v3, v173
	v_lshl_add_u64 v[2:3], s[34:35], 0, v[2:3]
	v_and_b32_e32 v34, 48, v6
	v_mov_b32_e32 v35, v173
	v_lshl_add_u64 v[2:3], v[34:35], 4, v[2:3]
	global_load_dword v157, v[4:5], off
	global_load_dwordx4 v[80:83], v[2:3], off
	global_load_dwordx4 v[76:79], v[2:3], off offset:1024
	global_load_dwordx4 v[72:75], v[2:3], off offset:2048
	global_load_dwordx4 v[68:71], v[2:3], off offset:3072
	v_lshrrev_b32_e32 v2, 2, v6
	v_and_b32_e32 v4, 12, v2
	v_or_b32_e32 v2, s19, v4
	v_readlane_b32 s48, v237, 4
	v_or_b32_e32 v2, s22, v2
	v_mov_b32_e32 v3, v173
	v_readlane_b32 s54, v237, 10
	v_readlane_b32 s55, v237, 11
	v_lshlrev_b32_e32 v7, 3, v36
	s_lshl_b32 s94, s25, 5
	v_lshl_add_u64 v[2:3], v[2:3], 2, s[54:55]
	v_lshl_add_u64 v[0:1], v[0:1], 0, s[94:95]
	global_load_dwordx4 v[64:67], v[2:3], off
	v_lshlrev_b32_e32 v2, 1, v7
	v_mov_b32_e32 v3, v173
	s_add_u32 s0, s86, s94
	v_lshl_add_u64 v[2:3], v[0:1], 0, v[2:3]
	s_addc_u32 s1, s87, 0
	v_lshlrev_b32_e32 v120, 1, v4
	v_mov_b32_e32 v121, v173
	v_lshl_add_u64 v[0:1], s[0:1], 0, v[120:121]
	v_add_co_u32_e32 v4, vcc, s92, v2
	v_add_u32_e32 v16, s23, v160
	s_nop 0
	v_addc_co_u32_e32 v5, vcc, 0, v3, vcc
	v_mad_i64_i32 v[6:7], s[0:1], v16, s66, v[0:1]
	v_add_co_u32_e32 v8, vcc, s92, v6
	v_add_u32_e32 v17, s24, v160
	s_nop 0
	v_addc_co_u32_e32 v9, vcc, 0, v7, vcc
	global_load_dwordx4 v[48:51], v[4:5], off
	global_load_dwordx2 v[152:153], v[6:7], off offset:2048
	v_mad_i64_i32 v[4:5], s[0:1], v17, s66, v[0:1]
	v_add_co_u32_e32 v6, vcc, s92, v4
	s_mov_b32 s0, 0x32000
	s_nop 0
	v_addc_co_u32_e32 v7, vcc, 0, v5, vcc
	v_or_b32_e32 v10, 16, v160
	global_load_dwordx2 v[112:113], v[4:5], off offset:2048
	v_add_co_u32_e32 v4, vcc, s0, v2
	v_add_u32_e32 v18, s23, v10
	s_nop 0
	v_addc_co_u32_e32 v5, vcc, 0, v3, vcc
	v_mad_i64_i32 v[6:7], s[0:1], v18, s66, v[0:1]
	v_add_co_u32_e32 v8, vcc, s92, v6
	v_add_u32_e32 v33, s24, v10
	s_nop 0
	v_addc_co_u32_e32 v9, vcc, 0, v7, vcc
	global_load_dwordx4 v[108:111], v[4:5], off
	global_load_dwordx2 v[144:145], v[6:7], off offset:2048
	v_mad_i64_i32 v[4:5], s[0:1], v33, s66, v[0:1]
	v_add_co_u32_e32 v6, vcc, 0x2000, v4
	s_mov_b64 s[0:1], 0x2000
	s_nop 0
	v_addc_co_u32_e32 v7, vcc, 0, v5, vcc
	global_load_dwordx2 v[140:141], v[4:5], off offset:2048
	v_cndmask_b32_e64 v4, 0, 1, s[44:45]
	v_lshl_add_u64 v[2:3], v[2:3], 0, s[0:1]
	v_cmp_ne_u32_e64 s[0:1], 1, v4
	v_or_b32_e32 v4, 32, v160
	s_andn2_b64 vcc, exec, s[44:45]
	v_add_u32_e32 v165, s23, v4
	v_add_u32_e32 v164, s24, v4
	v_readlane_b32 s49, v237, 5
	v_readlane_b32 s50, v237, 6
	v_readlane_b32 s51, v237, 7
	v_readlane_b32 s52, v237, 8
	v_readlane_b32 s53, v237, 9
	v_readlane_b32 s56, v237, 12
	v_readlane_b32 s57, v237, 13
	v_readlane_b32 s58, v237, 14
	v_readlane_b32 s59, v237, 15
	v_readlane_b32 s60, v237, 16
	v_readlane_b32 s61, v237, 17
	v_readlane_b32 s62, v237, 18
	v_readlane_b32 s63, v237, 19
	s_cbranch_vccnz .LBB0_782
	v_add_co_u32_e32 v4, vcc, 0x60000, v2
	v_mad_i64_i32 v[6:7], s[26:27], v165, s66, v[0:1]
	s_nop 0
	v_addc_co_u32_e32 v5, vcc, 0, v3, vcc
	v_add_co_u32_e32 v8, vcc, 0x2000, v6
	global_load_dwordx4 v[104:107], v[4:5], off
	global_load_dwordx2 v[136:137], v[6:7], off offset:2048
	v_addc_co_u32_e32 v9, vcc, 0, v7, vcc
	v_mad_i64_i32 v[4:5], s[26:27], v164, s66, v[0:1]
	v_add_co_u32_e32 v6, vcc, 0x2000, v4
	s_nop 1
	v_addc_co_u32_e32 v7, vcc, 0, v5, vcc
	global_load_dwordx2 v[132:133], v[4:5], off offset:2048
